# attention: partial-softmax max reduction and rescale decision hoisted from after the last PV MFMA into earlier PV MFMA shadows
# baseline (speedup 1.0000x reference)
; __device__ __forceinline__ void finishSM(f32x16& p0, f32x16& p1, float alpha, float& l_reg, bf16x8& pa0, bf16x8& pa1, bf16x8& pa2, bf16x8& pa3) {
; #pragma unroll
;     for (int r = 0; r < 16; ++r) p1[r] = __builtin_amdgcn_exp2f(p1[r]);
;     float ps = 0;
; #pragma unroll
;     for (int r = 0; r < 16; ++r) ps += p0[r];
; #pragma unroll
;     for (int r = 0; r < 16; ++r) ps += p1[r];
;     { auto rr = __builtin_amdgcn_permlane32_swap(__float_as_uint(ps), __float_as_uint(ps), false, false);
;       ps = __uint_as_float(rr[0]) + __uint_as_float(rr[1]); }
;     l_reg = l_reg * alpha + ps;
;     ...
;     PK4(p0, 0, pa0); PK4(p0, 8, pa1); PK4(p1, 0, pa2); PK4(p1, 8, pa3);
; __device__ __forceinline__ void qkt(f32x16& p0, f32x16& p1, const char* Kn, const bf16x8* qr, int r32, int hi) {
;     const char* Kr = Kn + KR_OFF;
;     p0 = f32x16{}; p1 = f32x16{};
;     __builtin_amdgcn_s_setprio(1);
; #pragma unroll
;     for (int d0 = 0; d0 < 8; ++d0) { const int cb = (d0 * 16 + hi * 8) * 2;
;         const bf16x8 b0 = *reinterpret_cast<const bf16x8*>(Kn + KNSWZ(r32, cb));
;         const bf16x8 b1 = *reinterpret_cast<const bf16x8*>(Kn + KNSWZ(32 + r32, cb));
;         p0 = __builtin_amdgcn_mfma_f32_32x32x16_bf16(b0, qr[d0], p0, 0, 0, 0);
;         p1 = __builtin_amdgcn_mfma_f32_32x32x16_bf16(b1, qr[d0], p1, 0, 0, 0); }
; #pragma unroll
;     for (int d0 = 0; d0 < 4; ++d0) { const int cb = (d0 * 16 + hi * 8) * 2;
;         const bf16x8 b0 = *reinterpret_cast<const bf16x8*>(Kr + KRSWZ(r32, cb));
;         const bf16x8 b1 = *reinterpret_cast<const bf16x8*>(Kr + KRSWZ(32 + r32, cb));
;         p0 = __builtin_amdgcn_mfma_f32_32x32x16_bf16(b0, qr[8 + d0], p0, 0, 0, 0);
;         p1 = __builtin_amdgcn_mfma_f32_32x32x16_bf16(b1, qr[8 + d0], p1, 0, 0, 0); }
; }
.LBB0_216:
	s_mul_i32 s0, s9, 0x6000
	s_add_i32 s14, s0, 0
	s_lshl_b32 s13, s9, 14
	s_add_i32 s16, s14, s6
	s_add_i32 s17, s7, s13
	s_add_i32 s18, s14, s8
	s_mov_b32 s13, s10
	s_mov_b32 s10, s15
	s_mul_i32 s0, s13, 0x6000
	s_add_i32 s0, s0, 0
	s_setprio 1
	v_add_u32_e32 v84, s0, v207
	ds_read_b128 v[80:83], v84
	ds_read_b128 v[84:87], v84 offset:8192
	v_add_u32_e32 v168, s0, v210
	ds_read_b128 v[196:199], v168
	ds_read_b128 v[168:171], v168 offset:8192
	v_add_u32_e32 v184, s0, v218
	s_waitcnt lgkmcnt(0)
	v_mfma_f32_32x32x16_bf16 v[96:111], v[80:83], v[156:159], 0
	v_mfma_f32_32x32x16_bf16 v[80:95], v[84:87], v[156:159], 0
	v_mfma_f32_32x32x16_bf16 v[96:111], v[196:199], v[152:155], v[96:111]
	v_mfma_f32_32x32x16_bf16 v[80:95], v[168:171], v[152:155], v[80:95]
	ds_read_b128 v[168:171], v184
	ds_read_b128 v[196:199], v184 offset:8192
	v_add_u32_e32 v184, s0, v221
	s_mov_b32 m0, s16
	s_add_u32 s100, s72, 0x26500000
	s_addc_u32 s101, s73, 0
	global_load_lds_dwordx4 v178, s[100:101]
	s_waitcnt lgkmcnt(0)
	v_mfma_f32_32x32x16_bf16 v[96:111], v[168:171], v[148:151], v[96:111]
	v_mfma_f32_32x32x16_bf16 v[80:95], v[196:199], v[148:151], v[80:95]
	ds_read_b128 v[168:171], v184
	ds_read_b128 v[196:199], v184 offset:8192
	v_add_u32_e32 v184, s0, v222
	s_waitcnt lgkmcnt(0)
	v_mfma_f32_32x32x16_bf16 v[96:111], v[168:171], v[144:147], v[96:111]
	v_mfma_f32_32x32x16_bf16 v[80:95], v[196:199], v[144:147], v[80:95]
	ds_read_b128 v[168:171], v184
	ds_read_b128 v[196:199], v184 offset:8192
	v_add_u32_e32 v184, s0, v223
	s_add_i32 m0, s16, 0x400
	s_nop 0
	global_load_lds_dwordx4 v180, s[100:101]
	s_waitcnt lgkmcnt(0)
	v_mfma_f32_32x32x16_bf16 v[96:111], v[168:171], v[140:143], v[96:111]
	v_mfma_f32_32x32x16_bf16 v[80:95], v[196:199], v[140:143], v[80:95]
	ds_read_b128 v[168:171], v184
	ds_read_b128 v[196:199], v184 offset:8192
	v_add_u32_e32 v184, s0, v224
	v_exp_f32_e32 v233, v73
	s_waitcnt lgkmcnt(0)
	v_mfma_f32_32x32x16_bf16 v[96:111], v[168:171], v[136:139], v[96:111]
	v_mfma_f32_32x32x16_bf16 v[80:95], v[196:199], v[136:139], v[80:95]
	ds_read_b128 v[168:171], v184
	ds_read_b128 v[196:199], v184 offset:8192
	v_add_u32_e32 v184, s0, v225
	s_mov_b32 m0, s17
	s_add_u32 s100, s72, 0x26500100
	s_addc_u32 s101, s73, 0
	global_load_lds_dwordx4 v176, s[100:101]
	v_exp_f32_e32 v250, v74
	s_waitcnt lgkmcnt(0)
	v_mfma_f32_32x32x16_bf16 v[96:111], v[168:171], v[132:135], v[96:111]
	v_mfma_f32_32x32x16_bf16 v[80:95], v[196:199], v[132:135], v[80:95]
	ds_read_b128 v[168:171], v184
	ds_read_b128 v[196:199], v184 offset:8192
	v_add_u32_e32 v184, s0, v226
	v_exp_f32_e32 v200, v75
	s_waitcnt lgkmcnt(0)
	v_mfma_f32_32x32x16_bf16 v[96:111], v[168:171], v[128:131], v[96:111]
	v_mfma_f32_32x32x16_bf16 v[80:95], v[196:199], v[128:131], v[80:95]
	ds_read_b128 v[168:171], v184 offset:16384
	ds_read_b128 v[196:199], v184 offset:20480
	v_add_u32_e32 v184, s0, v227
	s_add_i32 m0, s17, 0x400
	s_add_u32 s100, s72, 0x26500180
	s_addc_u32 s101, s73, 0
	global_load_lds_dwordx4 v176, s[100:101]
	v_exp_f32_e32 v195, v76
	s_waitcnt lgkmcnt(0)
	v_mfma_f32_32x32x16_bf16 v[96:111], v[168:171], v[124:127], v[96:111]
	v_mfma_f32_32x32x16_bf16 v[80:95], v[196:199], v[124:127], v[80:95]
	ds_read_b128 v[168:171], v184 offset:16384
	ds_read_b128 v[196:199], v184 offset:20480
	v_add_u32_e32 v184, s0, v228
	v_exp_f32_e32 v172, v77
	s_waitcnt lgkmcnt(0)
	v_mfma_f32_32x32x16_bf16 v[96:111], v[168:171], v[120:123], v[96:111]
	v_mfma_f32_32x32x16_bf16 v[80:95], v[196:199], v[120:123], v[80:95]
	ds_read_b128 v[168:171], v184 offset:16384
	ds_read_b128 v[196:199], v184 offset:20480
	v_add_u32_e32 v184, s0, v229
	s_add_i32 m0, s18, 0x4000
	s_add_u32 s100, s72, 0x21204000
	s_addc_u32 s101, s73, 0
	global_load_lds_dwordx4 v174, s[100:101]
	v_exp_f32_e32 v173, v78
	s_waitcnt lgkmcnt(0)
	v_mfma_f32_32x32x16_bf16 v[96:111], v[168:171], v[116:119], v[96:111]
	v_mfma_f32_32x32x16_bf16 v[80:95], v[196:199], v[116:119], v[80:95]
	ds_read_b128 v[168:171], v184 offset:16384
	ds_read_b128 v[196:199], v184 offset:20480
	v_exp_f32_e32 v184, v68
	v_exp_f32_e32 v79, v79
	s_waitcnt lgkmcnt(0)
	v_mfma_f32_32x32x16_bf16 v[96:111], v[168:171], v[112:115], v[96:111]
	v_exp_f32_e32 v168, v64
	v_add_f32_e32 v64, 0, v247
	v_add_f32_e32 v64, v249, v64
	v_add_f32_e32 v64, v245, v64
	v_add_f32_e32 v64, v248, v64
	v_add_f32_e32 v64, v244, v64
	v_add_f32_e32 v64, v246, v64
	v_add_f32_e32 v64, v242, v64
	v_add_f32_e32 v64, v243, v64
	v_add_f32_e32 v64, v239, v64
	v_add_f32_e32 v64, v241, v64
	v_add_f32_e32 v64, v238, v64
	v_add_f32_e32 v64, v240, v64
	v_add_f32_e32 v64, v235, v64
	v_exp_f32_e32 v169, v65
	v_add_f32_e32 v64, v237, v64
	v_exp_f32_e32 v170, v66
	v_add_f32_e32 v64, v234, v64
	v_exp_f32_e32 v171, v67
	v_add_f32_e32 v64, v236, v64
	v_add_f32_e32 v64, v168, v64
	v_mfma_f32_32x32x16_bf16 v[80:95], v[196:199], v[112:115], v[80:95]
	v_exp_f32_e32 v196, v69
	v_add_f32_e32 v64, v169, v64
	v_exp_f32_e32 v197, v70
	v_add_f32_e32 v64, v170, v64
	v_exp_f32_e32 v198, v71
	v_add_f32_e32 v64, v171, v64
	v_exp_f32_e32 v199, v72
	v_add_f32_e32 v64, v184, v64
	v_add_f32_e32 v64, v196, v64
	v_add_f32_e32 v64, v197, v64
	v_add_f32_e32 v64, v198, v64
	v_add_f32_e32 v64, v199, v64
	v_add_f32_e32 v64, v233, v64
	v_add_f32_e32 v64, v250, v64
	v_add_f32_e32 v64, v200, v64
	v_add_f32_e32 v64, v195, v64
	v_add_f32_e32 v64, v172, v64
	v_add_f32_e32 v64, v173, v64
	v_add_f32_e32 v231, v79, v64
	v_mov_b32_e32 v232, v231
	v_cvt_pk_bf16_f32 v64, v247, v249
	v_cvt_pk_bf16_f32 v65, v245, v248
	v_cvt_pk_bf16_f32 v66, v244, v246
	s_nop 1
	v_permlane32_swap_b32_e32 v231, v232
	v_cvt_pk_bf16_f32 v67, v242, v243
	v_permlane32_swap_b32_e32 v64, v66
	v_cvt_pk_bf16_f32 v68, v239, v241
	v_cvt_pk_bf16_f32 v69, v238, v240
	v_cvt_pk_bf16_f32 v70, v235, v237
	v_cvt_pk_bf16_f32 v71, v234, v236
	v_cvt_pk_bf16_f32 v72, v168, v169
	v_cvt_pk_bf16_f32 v73, v170, v171
	v_cvt_pk_bf16_f32 v74, v184, v196
	v_cvt_pk_bf16_f32 v75, v197, v198
	v_cvt_pk_bf16_f32 v76, v199, v233
	v_cvt_pk_bf16_f32 v77, v250, v200
	v_cvt_pk_bf16_f32 v78, v195, v172
	v_cvt_pk_bf16_f32 v79, v173, v79
	v_permlane32_swap_b32_e32 v65, v67
	v_permlane32_swap_b32_e32 v68, v70
	v_permlane32_swap_b32_e32 v69, v71
	v_permlane32_swap_b32_e32 v72, v74
	v_permlane32_swap_b32_e32 v73, v75
	v_permlane32_swap_b32_e32 v76, v78
	v_permlane32_swap_b32_e32 v77, v79
	s_setprio 0
	s_lshl_b32 s15, s15, 14
	v_add_u32_e32 v172, s15, v205
	ds_read_b64_tr_b16 v[168:169], v172 offset:0
	ds_read_b64_tr_b16 v[170:171], v172 offset:0x800
	ds_read_b64_tr_b16 v[196:197], v172 offset:0x1000
	ds_read_b64_tr_b16 v[198:199], v172 offset:0x1800
	ds_read_b64_tr_b16 v[234:235], v172 offset:0x2000
	ds_read_b64_tr_b16 v[236:237], v172 offset:0x2800
	ds_read_b64_tr_b16 v[238:239], v172 offset:0x3000
	ds_read_b64_tr_b16 v[240:241], v172 offset:0x3800
	s_waitcnt lgkmcnt(0)
; #define SBAR() __builtin_amdgcn_sched_barrier(0)
; template <bool FIRST>
; __device__ __forceinline__ void partialSM(f32x16& p0, f32x16& p1, float& m_reg, float& mn, float& alpha) {
;     float pmax = p0[0];
; #pragma unroll
;     for (int r = 1; r < 16; ++r) pmax = fmaxf(pmax, p0[r]);
; #pragma unroll
;     for (int r = 0; r < 16; ++r) pmax = fmaxf(pmax, p1[r]);
;     { auto rr = __builtin_amdgcn_permlane32_swap(__float_as_uint(pmax), __float_as_uint(pmax), false, false);
;       pmax = fmaxf(__uint_as_float(rr[0]), __uint_as_float(rr[1])); }
;     if (FIRST) { mn = (fabsf(pmax) <= THRL) ? 0.f : pmax; m_reg = mn; alpha = 1.f; }
;     else if (__builtin_expect(__all(pmax - m_reg <= THRL), 1)) { mn = m_reg; alpha = 1.f; }
;     else { mn = fmaxf(m_reg, pmax); alpha = __builtin_amdgcn_exp2f(m_reg - mn); m_reg = mn; }
;     if (!__builtin_expect(__all(mn == 0.f), 1)) {
; template <int D0> __device__ __forceinline__ void pv_one(f32x16& od, int vb, bf16x8 pa0, bf16x8 pa1, bf16x8 pa2, bf16x8 pa3) {
;     const s16x4 l0 = tr_read<v_rd_off(D0, 0, 0)>(vb), h0 = tr_read<v_rd_off(D0, 0, 1)>(vb), l1 = tr_read<v_rd_off(D0, 1, 0)>(vb), h1 = tr_read<v_rd_off(D0, 1, 1)>(vb);
;     const s16x4 l2 = tr_read<v_rd_off(D0, 2, 0)>(vb), h2 = tr_read<v_rd_off(D0, 2, 1)>(vb), l3 = tr_read<v_rd_off(D0, 3, 0)>(vb), h3 = tr_read<v_rd_off(D0, 3, 1)>(vb);
;     asm volatile("s_waitcnt lgkmcnt(0)" ::: "memory"); SBAR();
;     ...
;     od = __builtin_amdgcn_mfma_f32_32x32x16_bf16(pa0, PK(l0, h0), od, 0, 0, 0);
;     od = __builtin_amdgcn_mfma_f32_32x32x16_bf16(pa1, PK(l1, h1), od, 0, 0, 0);
;     od = __builtin_amdgcn_mfma_f32_32x32x16_bf16(pa2, PK(l2, h2), od, 0, 0, 0);
;     od = __builtin_amdgcn_mfma_f32_32x32x16_bf16(pa3, PK(l3, h3), od, 0, 0, 0);
;     ...
; }
; __device__ __forceinline__ void pv_d0(f32x16* o, int vb, bf16x8 pa0, bf16x8 pa1, bf16x8 pa2, bf16x8 pa3) {
;     pv_one<0>(o[0], vb, pa0, pa1, pa2, pa3); pv_one<1>(o[1], vb, pa0, pa1, pa2, pa3); pv_one<2>(o[2], vb, pa0, pa1, pa2, pa3); pv_one<3>(o[3], vb, pa0, pa1, pa2, pa3);
	s_nop 0
	v_mfma_f32_32x32x16_bf16 v[0:15], v[64:67], v[168:171], v[0:15]
	ds_read_b64_tr_b16 v[168:169], v172 offset:0x200
	ds_read_b64_tr_b16 v[170:171], v172 offset:0xa00
	v_mfma_f32_32x32x16_bf16 v[0:15], v[68:71], v[196:199], v[0:15]
	ds_read_b64_tr_b16 v[196:197], v172 offset:0x1200
	ds_read_b64_tr_b16 v[198:199], v172 offset:0x1a00
	v_mfma_f32_32x32x16_bf16 v[0:15], v[72:75], v[234:237], v[0:15]
	ds_read_b64_tr_b16 v[234:235], v172 offset:0x2200
	ds_read_b64_tr_b16 v[236:237], v172 offset:0x2a00
	v_mfma_f32_32x32x16_bf16 v[0:15], v[76:79], v[238:241], v[0:15]
	ds_read_b64_tr_b16 v[238:239], v172 offset:0x3200
	ds_read_b64_tr_b16 v[240:241], v172 offset:0x3a00
	s_waitcnt lgkmcnt(0)
	v_mfma_f32_32x32x16_bf16 v[48:63], v[64:67], v[168:171], v[48:63]
	v_max_f32_e32 v186, v97, v97
	v_max_f32_e32 v187, v96, v96
	v_max_f32_e32 v186, v187, v186
	v_max3_f32 v186, v186, v98, v99
	v_max3_f32 v186, v186, v100, v101
	v_max3_f32 v186, v186, v102, v103
	v_max3_f32 v186, v186, v104, v105
	ds_read_b64_tr_b16 v[168:169], v172 offset:0x400
	ds_read_b64_tr_b16 v[170:171], v172 offset:0xc00
	v_mfma_f32_32x32x16_bf16 v[48:63], v[68:71], v[196:199], v[48:63]
	v_max3_f32 v186, v186, v106, v107
	v_max3_f32 v186, v186, v108, v109
	v_max3_f32 v186, v186, v110, v111
	v_max3_f32 v186, v186, v80, v81
	v_max3_f32 v186, v186, v82, v83
	v_max3_f32 v186, v186, v84, v85
	v_max3_f32 v186, v186, v86, v87
	ds_read_b64_tr_b16 v[196:197], v172 offset:0x1400
	ds_read_b64_tr_b16 v[198:199], v172 offset:0x1c00
	v_mfma_f32_32x32x16_bf16 v[48:63], v[72:75], v[234:237], v[48:63]
	ds_read_b64_tr_b16 v[234:235], v172 offset:0x2400
	ds_read_b64_tr_b16 v[236:237], v172 offset:0x2c00
	v_mfma_f32_32x32x16_bf16 v[48:63], v[76:79], v[238:241], v[48:63]
	ds_read_b64_tr_b16 v[238:239], v172 offset:0x3400
	ds_read_b64_tr_b16 v[240:241], v172 offset:0x3c00
	s_waitcnt lgkmcnt(0)
	v_mfma_f32_32x32x16_bf16 v[32:47], v[64:67], v[168:171], v[32:47]
	v_max3_f32 v186, v186, v88, v89
	v_max3_f32 v186, v186, v90, v91
	v_max3_f32 v186, v186, v92, v93
	v_max3_f32 v186, v186, v94, v95
	v_mov_b32_e32 v187, v186
	s_nop 1
	v_permlane32_swap_b32_e32 v186, v187
	v_max_f32_e32 v187, v187, v187
	v_max_f32_e32 v186, v186, v186
	ds_read_b64_tr_b16 v[168:169], v172 offset:0x600
	ds_read_b64_tr_b16 v[170:171], v172 offset:0xe00
	v_mfma_f32_32x32x16_bf16 v[32:47], v[68:71], v[196:199], v[32:47]
	v_max_f32_e32 v186, v186, v187
	v_sub_f32_e32 v187, v186, v182
	s_mov_b32 s0, 0x41300000
	v_cmp_ge_f32_e32 vcc, s0, v187
	s_cmp_eq_u64 vcc, exec
	v_max_f32_e32 v187, v182, v182
	s_cselect_b64 vcc, -1, 0
	v_max_f32_e32 v186, v187, v186
	v_cndmask_b32_e32 v184, v186, v182, vcc
	v_cmp_eq_f32_e64 s[0:1], 0, v184
	s_cmp_eq_u64 s[0:1], exec
	s_cbranch_scc0 .LBB0_228
.LBB0_217:
	v_sub_f32_e32 v186, v182, v186
	v_exp_f32_e32 v186, v186
	s_nop 0
	v_cndmask_b32_e64 v233, v186, 1.0, vcc
	ds_read_b64_tr_b16 v[196:197], v172 offset:0x1600
	ds_read_b64_tr_b16 v[198:199], v172 offset:0x1e00
	v_mfma_f32_32x32x16_bf16 v[32:47], v[72:75], v[234:237], v[32:47]
	ds_read_b64_tr_b16 v[234:235], v172 offset:0x2600
	ds_read_b64_tr_b16 v[236:237], v172 offset:0x2e00
	v_mfma_f32_32x32x16_bf16 v[32:47], v[76:79], v[238:241], v[32:47]
	ds_read_b64_tr_b16 v[238:239], v172 offset:0x3600
	ds_read_b64_tr_b16 v[240:241], v172 offset:0x3e00
	s_waitcnt lgkmcnt(0)
	v_mfma_f32_32x32x16_bf16 v[16:31], v[64:67], v[168:171], v[16:31]
	v_mfma_f32_32x32x16_bf16 v[16:31], v[68:71], v[196:199], v[16:31]
	v_mfma_f32_32x32x16_bf16 v[16:31], v[72:75], v[234:237], v[16:31]
	v_mfma_f32_32x32x16_bf16 v[16:31], v[76:79], v[238:241], v[16:31]
	v_cmp_gt_f32_e32 vcc, 1.0, v233
	s_cbranch_vccz .LBB0_221
	s_nop 7
	s_and_saveexec_b64 s[0:1], s[38:39]
	ds_write_b32 v202, v233 offset:128
	s_or_b64 exec, exec, s[0:1]
	s_waitcnt lgkmcnt(0)
	v_add_u32_e32 v76, s5, v160
	ds_read_b128 v[64:67], v76 offset:224
	ds_read_b128 v[68:71], v76 offset:192
	ds_read_b128 v[72:75], v76 offset:160
	ds_read_b128 v[76:79], v76 offset:128
	s_waitcnt lgkmcnt(0)
	v_pk_mul_f32 v[12:13], v[12:13], v[64:65]
	v_pk_mul_f32 v[8:9], v[8:9], v[68:69]
	v_pk_mul_f32 v[4:5], v[4:5], v[72:73]
	v_pk_mul_f32 v[14:15], v[14:15], v[66:67]
	v_pk_mul_f32 v[10:11], v[10:11], v[70:71]
	v_pk_mul_f32 v[6:7], v[6:7], v[74:75]
	v_pk_mul_f32 v[2:3], v[2:3], v[78:79]
	v_pk_mul_f32 v[0:1], v[0:1], v[76:77]
	v_pk_mul_f32 v[60:61], v[60:61], v[64:65]
	v_pk_mul_f32 v[56:57], v[56:57], v[68:69]
	v_pk_mul_f32 v[52:53], v[52:53], v[72:73]
	v_pk_mul_f32 v[62:63], v[62:63], v[66:67]
	v_pk_mul_f32 v[58:59], v[58:59], v[70:71]
	v_pk_mul_f32 v[54:55], v[54:55], v[74:75]
	v_pk_mul_f32 v[50:51], v[50:51], v[78:79]
	v_pk_mul_f32 v[48:49], v[48:49], v[76:77]
	v_pk_mul_f32 v[44:45], v[44:45], v[64:65]
	v_pk_mul_f32 v[40:41], v[40:41], v[68:69]
	v_pk_mul_f32 v[36:37], v[36:37], v[72:73]
	v_pk_mul_f32 v[46:47], v[46:47], v[66:67]
	v_pk_mul_f32 v[42:43], v[42:43], v[70:71]
	v_pk_mul_f32 v[38:39], v[38:39], v[74:75]
	v_pk_mul_f32 v[34:35], v[34:35], v[78:79]
	v_pk_mul_f32 v[32:33], v[32:33], v[76:77]
	v_pk_mul_f32 v[28:29], v[28:29], v[64:65]
	v_pk_mul_f32 v[24:25], v[24:25], v[68:69]
	v_pk_mul_f32 v[20:21], v[20:21], v[72:73]
	v_pk_mul_f32 v[30:31], v[30:31], v[66:67]
	v_pk_mul_f32 v[26:27], v[26:27], v[70:71]
	v_pk_mul_f32 v[22:23], v[22:23], v[74:75]
	v_pk_mul_f32 v[18:19], v[18:19], v[78:79]
	v_pk_mul_f32 v[16:17], v[16:17], v[76:77]
; #define SBAR() __builtin_amdgcn_sched_barrier(0)
; #define WAIT_BAR() asm volatile("s_waitcnt vmcnt(0) lgkmcnt(0)\n\ts_barrier" ::: "memory")
; #define RESC(a) do { if (__any((a) < 1.f)) { if (hi == 0) al_l[r32] = (a); asm volatile("s_waitcnt lgkmcnt(0)" ::: "memory"); \
;     _Pragma("unroll") for (int d = 0; d < 4; ++d) _Pragma("unroll") for (int r = 0; r < 16; ++r) o[d][r] *= al_l[crow(r, hi)]; } } while (0)
; #define ROT() do { const int t_ = s_prev; s_prev = s_cur; s_cur = s_next; s_next = t_; } while (0)
; __device__ __forceinline__ void qkt(f32x16& p0, f32x16& p1, const char* Kn, const bf16x8* qr, int r32, int hi) {
;     const char* Kr = Kn + KR_OFF;
;     p0 = f32x16{}; p1 = f32x16{};
;     __builtin_amdgcn_s_setprio(1);
; #pragma unroll
;     for (int d0 = 0; d0 < 8; ++d0) { const int cb = (d0 * 16 + hi * 8) * 2;
;         const bf16x8 b0 = *reinterpret_cast<const bf16x8*>(Kn + KNSWZ(r32, cb));
;         const bf16x8 b1 = *reinterpret_cast<const bf16x8*>(Kn + KNSWZ(32 + r32, cb));
;         p0 = __builtin_amdgcn_mfma_f32_32x32x16_bf16(b0, qr[d0], p0, 0, 0, 0);
;         p1 = __builtin_amdgcn_mfma_f32_32x32x16_bf16(b1, qr[d0], p1, 0, 0, 0); }
; #pragma unroll
;     for (int d0 = 0; d0 < 4; ++d0) { const int cb = (d0 * 16 + hi * 8) * 2;
;         const bf16x8 b0 = *reinterpret_cast<const bf16x8*>(Kr + KRSWZ(r32, cb));
;         const bf16x8 b1 = *reinterpret_cast<const bf16x8*>(Kr + KRSWZ(32 + r32, cb));
;         p0 = __builtin_amdgcn_mfma_f32_32x32x16_bf16(b0, qr[8 + d0], p0, 0, 0, 0);
;         p1 = __builtin_amdgcn_mfma_f32_32x32x16_bf16(b1, qr[8 + d0], p1, 0, 0, 0); }
; }
; __device__ __forceinline__ void attn_unit(const bf16_t* __restrict__ Qb, const bf16_t* __restrict__ Kn, const bf16_t* __restrict__ Vh, const bf16_t* __restrict__ Kr,
;                                           bf16_t* __restrict__ Ob, int seq, char* lds, int wv_) { LAUNDER_IDS;
;     ...
;         RESC(alB); WAIT_BAR(); ROT();
;         DMA(j + 2, s_next); SBAR();
;         qkt(pA0, pA1, lds + OFF_K + s_cur * SLOT_K, qr, r32, hi);
.LBB0_221:
	v_exp_f32_e32 v182, v98
	v_exp_f32_e32 v172, v96
	v_exp_f32_e32 v173, v97
	v_exp_f32_e32 v195, v99
	v_exp_f32_e32 v196, v100
	v_exp_f32_e32 v197, v101
	v_exp_f32_e32 v198, v102
	v_exp_f32_e32 v199, v103
	v_exp_f32_e32 v200, v104
	v_exp_f32_e32 v234, v105
	v_exp_f32_e32 v235, v106
	v_exp_f32_e32 v236, v107
	v_exp_f32_e32 v237, v108
	v_exp_f32_e32 v238, v109
	v_exp_f32_e32 v239, v110
	v_exp_f32_e32 v240, v111
	s_mul_i32 s0, s10, 0x6000
	s_add_i32 s16, s0, 0
	s_add_i32 s17, s16, s6
	s_add_i32 s18, s16, s8
	s_waitcnt vmcnt(0) lgkmcnt(0)
	s_barrier
	s_add_i32 s15, s7, s15
	s_setprio 1
	v_add_u32_e32 v68, s14, v207
	ds_read_b128 v[64:67], v68
	ds_read_b128 v[68:71], v68 offset:8192
	v_add_u32_e32 v186, s14, v210
	ds_read_b128 v[168:171], v186
	ds_read_b128 v[186:189], v186 offset:8192
	s_waitcnt lgkmcnt(0)
	v_mfma_f32_32x32x16_bf16 v[96:111], v[64:67], v[156:159], 0
	v_mfma_f32_32x32x16_bf16 v[64:79], v[68:71], v[156:159], 0
	v_mfma_f32_32x32x16_bf16 v[96:111], v[168:171], v[152:155], v[96:111]
	v_mfma_f32_32x32x16_bf16 v[64:79], v[186:189], v[152:155], v[64:79]
	v_add_u32_e32 v186, s14, v218
	ds_read_b128 v[168:171], v186
	ds_read_b128 v[186:189], v186 offset:8192
	s_mov_b32 m0, s17
	s_add_u32 s100, s72, 0x26580000
	s_addc_u32 s101, s73, 0
	global_load_lds_dwordx4 v178, s[100:101]
	s_waitcnt lgkmcnt(0)
	v_mfma_f32_32x32x16_bf16 v[96:111], v[168:171], v[148:151], v[96:111]
	v_mfma_f32_32x32x16_bf16 v[64:79], v[186:189], v[148:151], v[64:79]
	v_add_u32_e32 v186, s14, v221
	ds_read_b128 v[168:171], v186
	ds_read_b128 v[186:189], v186 offset:8192
	s_waitcnt lgkmcnt(0)
	v_mfma_f32_32x32x16_bf16 v[96:111], v[168:171], v[144:147], v[96:111]
	v_mfma_f32_32x32x16_bf16 v[64:79], v[186:189], v[144:147], v[64:79]
	v_add_u32_e32 v186, s14, v222
	ds_read_b128 v[168:171], v186
	ds_read_b128 v[186:189], v186 offset:8192
	s_add_i32 m0, s17, 0x400
	s_nop 0
	global_load_lds_dwordx4 v180, s[100:101]
	v_exp_f32_e32 v190, v88
	s_waitcnt lgkmcnt(0)
	v_mfma_f32_32x32x16_bf16 v[96:111], v[168:171], v[140:143], v[96:111]
	v_mfma_f32_32x32x16_bf16 v[64:79], v[186:189], v[140:143], v[64:79]
	v_add_u32_e32 v186, s14, v223
	ds_read_b128 v[168:171], v186
	ds_read_b128 v[186:189], v186 offset:8192
	v_exp_f32_e32 v191, v89
	s_waitcnt lgkmcnt(0)
	v_mfma_f32_32x32x16_bf16 v[96:111], v[168:171], v[136:139], v[96:111]
	v_mfma_f32_32x32x16_bf16 v[64:79], v[186:189], v[136:139], v[64:79]
	v_add_u32_e32 v186, s14, v224
	ds_read_b128 v[168:171], v186
	ds_read_b128 v[186:189], v186 offset:8192
	s_mov_b32 m0, s15
	s_add_u32 s100, s72, 0x26580100
	s_addc_u32 s101, s73, 0
	global_load_lds_dwordx4 v176, s[100:101]
	v_exp_f32_e32 v192, v90
	s_waitcnt lgkmcnt(0)
	v_mfma_f32_32x32x16_bf16 v[96:111], v[168:171], v[132:135], v[96:111]
	v_mfma_f32_32x32x16_bf16 v[64:79], v[186:189], v[132:135], v[64:79]
	v_add_u32_e32 v186, s14, v225
	ds_read_b128 v[168:171], v186
	ds_read_b128 v[186:189], v186 offset:8192
	v_exp_f32_e32 v193, v91
	s_waitcnt lgkmcnt(0)
	v_mfma_f32_32x32x16_bf16 v[96:111], v[168:171], v[128:131], v[96:111]
	v_mfma_f32_32x32x16_bf16 v[64:79], v[186:189], v[128:131], v[64:79]
	v_add_u32_e32 v186, s14, v226
	ds_read_b128 v[168:171], v186 offset:16384
	ds_read_b128 v[186:189], v186 offset:20480
	s_add_i32 m0, s15, 0x400
	s_add_u32 s100, s72, 0x26580180
	s_addc_u32 s101, s73, 0
	global_load_lds_dwordx4 v176, s[100:101]
	v_exp_f32_e32 v241, v92
	s_waitcnt lgkmcnt(0)
	v_mfma_f32_32x32x16_bf16 v[96:111], v[168:171], v[124:127], v[96:111]
	v_mfma_f32_32x32x16_bf16 v[64:79], v[186:189], v[124:127], v[64:79]
	v_add_u32_e32 v186, s14, v227
	ds_read_b128 v[168:171], v186 offset:16384
	ds_read_b128 v[186:189], v186 offset:20480
	v_exp_f32_e32 v242, v93
	s_waitcnt lgkmcnt(0)
	v_mfma_f32_32x32x16_bf16 v[96:111], v[168:171], v[120:123], v[96:111]
	v_mfma_f32_32x32x16_bf16 v[64:79], v[186:189], v[120:123], v[64:79]
	v_add_u32_e32 v186, s14, v228
	ds_read_b128 v[168:171], v186 offset:16384
	ds_read_b128 v[186:189], v186 offset:20480
	s_add_i32 m0, s18, 0x4000
	s_add_u32 s100, s72, 0x21206000
	s_addc_u32 s101, s73, 0
	global_load_lds_dwordx4 v174, s[100:101]
	v_exp_f32_e32 v94, v94
	s_waitcnt lgkmcnt(0)
	v_mfma_f32_32x32x16_bf16 v[96:111], v[168:171], v[116:119], v[96:111]
	v_mfma_f32_32x32x16_bf16 v[64:79], v[186:189], v[116:119], v[64:79]
	v_add_u32_e32 v186, s14, v229
	ds_read_b128 v[168:171], v186 offset:16384
	ds_read_b128 v[186:189], v186 offset:20480
	v_exp_f32_e32 v95, v95
	s_waitcnt lgkmcnt(0)
; #define SBAR() __builtin_amdgcn_sched_barrier(0)
; __device__ __forceinline__ void finishSM(f32x16& p0, f32x16& p1, float alpha, float& l_reg, bf16x8& pa0, bf16x8& pa1, bf16x8& pa2, bf16x8& pa3) {
; #pragma unroll
;     for (int r = 0; r < 16; ++r) p1[r] = __builtin_amdgcn_exp2f(p1[r]);
;     float ps = 0;
; #pragma unroll
;     for (int r = 0; r < 16; ++r) ps += p0[r];
; #pragma unroll
;     for (int r = 0; r < 16; ++r) ps += p1[r];
;     { auto rr = __builtin_amdgcn_permlane32_swap(__float_as_uint(ps), __float_as_uint(ps), false, false);
;       ps = __uint_as_float(rr[0]) + __uint_as_float(rr[1]); }
;     l_reg = l_reg * alpha + ps;
;     ...
;     PK4(p0, 0, pa0); PK4(p0, 8, pa1); PK4(p1, 0, pa2); PK4(p1, 8, pa3);
; template <int D0> __device__ __forceinline__ void pv_one(f32x16& od, int vb, bf16x8 pa0, bf16x8 pa1, bf16x8 pa2, bf16x8 pa3) {
;     const s16x4 l0 = tr_read<v_rd_off(D0, 0, 0)>(vb), h0 = tr_read<v_rd_off(D0, 0, 1)>(vb), l1 = tr_read<v_rd_off(D0, 1, 0)>(vb), h1 = tr_read<v_rd_off(D0, 1, 1)>(vb);
;     const s16x4 l2 = tr_read<v_rd_off(D0, 2, 0)>(vb), h2 = tr_read<v_rd_off(D0, 2, 1)>(vb), l3 = tr_read<v_rd_off(D0, 3, 0)>(vb), h3 = tr_read<v_rd_off(D0, 3, 1)>(vb);
;     asm volatile("s_waitcnt lgkmcnt(0)" ::: "memory"); SBAR();
;     ...
;     od = __builtin_amdgcn_mfma_f32_32x32x16_bf16(pa0, PK(l0, h0), od, 0, 0, 0);
;     od = __builtin_amdgcn_mfma_f32_32x32x16_bf16(pa1, PK(l1, h1), od, 0, 0, 0);
;     od = __builtin_amdgcn_mfma_f32_32x32x16_bf16(pa2, PK(l2, h2), od, 0, 0, 0);
;     od = __builtin_amdgcn_mfma_f32_32x32x16_bf16(pa3, PK(l3, h3), od, 0, 0, 0);
;     ...
; }
; __device__ __forceinline__ void pv_d0(f32x16* o, int vb, bf16x8 pa0, bf16x8 pa1, bf16x8 pa2, bf16x8 pa3) {
;     pv_one<0>(o[0], vb, pa0, pa1, pa2, pa3); pv_one<1>(o[1], vb, pa0, pa1, pa2, pa3); pv_one<2>(o[2], vb, pa0, pa1, pa2, pa3); pv_one<3>(o[3], vb, pa0, pa1, pa2, pa3);
	v_mfma_f32_32x32x16_bf16 v[96:111], v[168:171], v[112:115], v[96:111]
	v_exp_f32_e32 v168, v80
	v_add_f32_e32 v80, 0, v172
	v_add_f32_e32 v80, v173, v80
	v_add_f32_e32 v80, v182, v80
	v_add_f32_e32 v80, v195, v80
	v_add_f32_e32 v80, v196, v80
	v_add_f32_e32 v80, v197, v80
	v_add_f32_e32 v80, v198, v80
	v_add_f32_e32 v80, v199, v80
	v_add_f32_e32 v80, v200, v80
	v_add_f32_e32 v80, v234, v80
	v_add_f32_e32 v80, v235, v80
	v_add_f32_e32 v80, v236, v80
	v_add_f32_e32 v80, v237, v80
	v_exp_f32_e32 v169, v81
	v_add_f32_e32 v80, v238, v80
	v_exp_f32_e32 v170, v82
	v_add_f32_e32 v80, v239, v80
	v_exp_f32_e32 v171, v83
	v_add_f32_e32 v80, v240, v80
	v_mfma_f32_32x32x16_bf16 v[64:79], v[186:189], v[112:115], v[64:79]
	v_exp_f32_e32 v186, v84
	v_add_f32_e32 v80, v168, v80
	v_exp_f32_e32 v187, v85
	v_add_f32_e32 v80, v169, v80
	v_exp_f32_e32 v188, v86
	v_add_f32_e32 v80, v170, v80
	v_exp_f32_e32 v189, v87
	v_add_f32_e32 v80, v171, v80
	v_add_f32_e32 v80, v186, v80
	v_add_f32_e32 v80, v187, v80
	v_add_f32_e32 v80, v188, v80
	v_add_f32_e32 v80, v189, v80
	v_add_f32_e32 v80, v190, v80
	v_add_f32_e32 v80, v191, v80
	v_add_f32_e32 v80, v192, v80
	v_add_f32_e32 v80, v193, v80
	v_add_f32_e32 v80, v241, v80
	v_add_f32_e32 v80, v242, v80
	v_add_f32_e32 v80, v94, v80
	v_add_f32_e32 v80, v95, v80
	v_mov_b32_e32 v81, v80
	v_cvt_pk_bf16_f32 v82, v172, v173
	v_cvt_pk_bf16_f32 v83, v182, v195
	v_cvt_pk_bf16_f32 v84, v196, v197
	s_nop 1
	v_permlane32_swap_b32_e32 v80, v81
	v_cvt_pk_bf16_f32 v85, v198, v199
	v_permlane32_swap_b32_e32 v82, v84
	v_cvt_pk_bf16_f32 v86, v200, v234
	v_cvt_pk_bf16_f32 v87, v235, v236
	v_cvt_pk_bf16_f32 v88, v237, v238
	v_cvt_pk_bf16_f32 v89, v239, v240
	v_cvt_pk_bf16_f32 v90, v168, v169
	v_cvt_pk_bf16_f32 v91, v170, v171
	v_cvt_pk_bf16_f32 v92, v186, v187
	v_cvt_pk_bf16_f32 v93, v188, v189
	v_cvt_pk_bf16_f32 v168, v190, v191
	v_cvt_pk_bf16_f32 v169, v192, v193
	v_cvt_pk_bf16_f32 v170, v241, v242
	v_cvt_pk_bf16_f32 v171, v94, v95
	v_permlane32_swap_b32_e32 v83, v85
	v_permlane32_swap_b32_e32 v86, v88
	v_permlane32_swap_b32_e32 v87, v89
	v_permlane32_swap_b32_e32 v90, v92
	v_permlane32_swap_b32_e32 v91, v93
	v_permlane32_swap_b32_e32 v168, v170
	v_permlane32_swap_b32_e32 v169, v171
	s_setprio 0
	v_lshl_add_u32 v94, s13, 14, v205
	ds_read_b64_tr_b16 v[186:187], v94 offset:0
	ds_read_b64_tr_b16 v[188:189], v94 offset:0x800
	ds_read_b64_tr_b16 v[190:191], v94 offset:0x1000
	ds_read_b64_tr_b16 v[192:193], v94 offset:0x1800
	ds_read_b64_tr_b16 v[196:197], v94 offset:0x2000
	ds_read_b64_tr_b16 v[198:199], v94 offset:0x2800
	ds_read_b64_tr_b16 v[234:235], v94 offset:0x3000
	ds_read_b64_tr_b16 v[236:237], v94 offset:0x3800
	s_waitcnt lgkmcnt(0)
	s_nop 0
	v_mfma_f32_32x32x16_bf16 v[0:15], v[82:85], v[186:189], v[0:15]
	ds_read_b64_tr_b16 v[186:187], v94 offset:0x200
	ds_read_b64_tr_b16 v[188:189], v94 offset:0xa00
	v_mfma_f32_32x32x16_bf16 v[0:15], v[86:89], v[190:193], v[0:15]
	ds_read_b64_tr_b16 v[190:191], v94 offset:0x1200
	ds_read_b64_tr_b16 v[192:193], v94 offset:0x1a00
	v_mfma_f32_32x32x16_bf16 v[0:15], v[90:93], v[196:199], v[0:15]
	ds_read_b64_tr_b16 v[196:197], v94 offset:0x2200
	ds_read_b64_tr_b16 v[198:199], v94 offset:0x2a00
	v_mfma_f32_32x32x16_bf16 v[0:15], v[168:171], v[234:237], v[0:15]
	ds_read_b64_tr_b16 v[234:235], v94 offset:0x3200
	ds_read_b64_tr_b16 v[236:237], v94 offset:0x3a00
	s_waitcnt lgkmcnt(0)
	v_mfma_f32_32x32x16_bf16 v[48:63], v[82:85], v[186:189], v[48:63]
	v_max_f32_e32 v241, v97, v97
	v_max_f32_e32 v242, v96, v96
	v_max_f32_e32 v241, v242, v241
	v_max3_f32 v241, v241, v98, v99
	v_max3_f32 v241, v241, v100, v101
	v_max3_f32 v241, v241, v102, v103
	v_max3_f32 v241, v241, v104, v105
	ds_read_b64_tr_b16 v[186:187], v94 offset:0x400
	ds_read_b64_tr_b16 v[188:189], v94 offset:0xc00
	v_mfma_f32_32x32x16_bf16 v[48:63], v[86:89], v[190:193], v[48:63]
	v_max3_f32 v241, v241, v106, v107
	v_max3_f32 v241, v241, v108, v109
	v_max3_f32 v241, v241, v110, v111
	v_max3_f32 v241, v241, v64, v65
	v_max3_f32 v241, v241, v66, v67
	v_max3_f32 v241, v241, v68, v69
	v_max3_f32 v241, v241, v70, v71
	ds_read_b64_tr_b16 v[190:191], v94 offset:0x1400
	ds_read_b64_tr_b16 v[192:193], v94 offset:0x1c00
	v_mfma_f32_32x32x16_bf16 v[48:63], v[90:93], v[196:199], v[48:63]
	ds_read_b64_tr_b16 v[196:197], v94 offset:0x2400
	ds_read_b64_tr_b16 v[198:199], v94 offset:0x2c00
	v_mfma_f32_32x32x16_bf16 v[48:63], v[168:171], v[234:237], v[48:63]
	ds_read_b64_tr_b16 v[234:235], v94 offset:0x3400
	ds_read_b64_tr_b16 v[236:237], v94 offset:0x3c00
	s_waitcnt lgkmcnt(0)
	v_mfma_f32_32x32x16_bf16 v[32:47], v[82:85], v[186:189], v[32:47]
	v_max3_f32 v241, v241, v72, v73
	v_max3_f32 v241, v241, v74, v75
	v_max3_f32 v241, v241, v76, v77
	v_max3_f32 v241, v241, v78, v79
	v_mov_b32_e32 v242, v241
	s_nop 1
	v_permlane32_swap_b32_e32 v241, v242
	v_max_f32_e32 v242, v242, v242
	v_max_f32_e32 v241, v241, v241
	ds_read_b64_tr_b16 v[186:187], v94 offset:0x600
	ds_read_b64_tr_b16 v[188:189], v94 offset:0xe00
	v_mfma_f32_32x32x16_bf16 v[32:47], v[86:89], v[190:193], v[32:47]
	v_max_f32_e32 v241, v241, v242
	v_sub_f32_e32 v242, v241, v184
	s_mov_b32 s0, 0x41300000
	v_cmp_ge_f32_e32 vcc, s0, v242
	s_cmp_eq_u64 vcc, exec
	v_max_f32_e32 v242, v184, v184
	s_cselect_b64 vcc, -1, 0
	v_max_f32_e32 v241, v242, v241
	v_cndmask_b32_e32 v182, v241, v184, vcc
	v_cmp_eq_f32_e64 s[0:1], 0, v182
	s_cmp_eq_u64 s[0:1], exec
	s_cbranch_scc0 .LBB0_229
; #define SBAR() __builtin_amdgcn_sched_barrier(0)
; template <int D0> __device__ __forceinline__ void pv_one(f32x16& od, int vb, bf16x8 pa0, bf16x8 pa1, bf16x8 pa2, bf16x8 pa3) {
;     const s16x4 l0 = tr_read<v_rd_off(D0, 0, 0)>(vb), h0 = tr_read<v_rd_off(D0, 0, 1)>(vb), l1 = tr_read<v_rd_off(D0, 1, 0)>(vb), h1 = tr_read<v_rd_off(D0, 1, 1)>(vb);
;     const s16x4 l2 = tr_read<v_rd_off(D0, 2, 0)>(vb), h2 = tr_read<v_rd_off(D0, 2, 1)>(vb), l3 = tr_read<v_rd_off(D0, 3, 0)>(vb), h3 = tr_read<v_rd_off(D0, 3, 1)>(vb);
;     asm volatile("s_waitcnt lgkmcnt(0)" ::: "memory"); SBAR();
;     ...
;     od = __builtin_amdgcn_mfma_f32_32x32x16_bf16(pa0, PK(l0, h0), od, 0, 0, 0);
;     od = __builtin_amdgcn_mfma_f32_32x32x16_bf16(pa1, PK(l1, h1), od, 0, 0, 0);
;     od = __builtin_amdgcn_mfma_f32_32x32x16_bf16(pa2, PK(l2, h2), od, 0, 0, 0);
;     od = __builtin_amdgcn_mfma_f32_32x32x16_bf16(pa3, PK(l3, h3), od, 0, 0, 0);
;     ...
; }
; __device__ __forceinline__ void pv_d0(f32x16* o, int vb, bf16x8 pa0, bf16x8 pa1, bf16x8 pa2, bf16x8 pa3) {
;     pv_one<0>(o[0], vb, pa0, pa1, pa2, pa3); pv_one<1>(o[1], vb, pa0, pa1, pa2, pa3); pv_one<2>(o[2], vb, pa0, pa1, pa2, pa3); pv_one<3>(o[3], vb, pa0, pa1, pa2, pa3);
.LBB0_222:
	v_sub_f32_e32 v241, v184, v241
	v_exp_f32_e32 v241, v241
	s_nop 0
	v_cndmask_b32_e64 v184, v241, 1.0, vcc
	ds_read_b64_tr_b16 v[190:191], v94 offset:0x1600
	ds_read_b64_tr_b16 v[192:193], v94 offset:0x1e00
	v_mfma_f32_32x32x16_bf16 v[32:47], v[90:93], v[196:199], v[32:47]
	ds_read_b64_tr_b16 v[196:197], v94 offset:0x2600
	ds_read_b64_tr_b16 v[198:199], v94 offset:0x2e00
	v_mfma_f32_32x32x16_bf16 v[32:47], v[168:171], v[234:237], v[32:47]
	ds_read_b64_tr_b16 v[234:235], v94 offset:0x3600
	ds_read_b64_tr_b16 v[236:237], v94 offset:0x3e00
	s_waitcnt lgkmcnt(0)
	v_mfma_f32_32x32x16_bf16 v[16:31], v[82:85], v[186:189], v[16:31]
	v_mfma_f32_32x32x16_bf16 v[16:31], v[86:89], v[190:193], v[16:31]
	v_mfma_f32_32x32x16_bf16 v[16:31], v[90:93], v[196:199], v[16:31]
	v_mfma_f32_32x32x16_bf16 v[16:31], v[168:171], v[234:237], v[16:31]
	v_cmp_gt_f32_e32 vcc, 1.0, v184
	s_cbranch_vccz .LBB0_226
	s_nop 7
	s_and_saveexec_b64 s[0:1], s[38:39]
	ds_write_b32 v202, v184 offset:128
	s_or_b64 exec, exec, s[0:1]
	s_waitcnt lgkmcnt(0)
	v_add_u32_e32 v94, s5, v160
	ds_read_b128 v[82:85], v94 offset:224
	ds_read_b128 v[86:89], v94 offset:192
	ds_read_b128 v[90:93], v94 offset:160
	ds_read_b128 v[168:171], v94 offset:128
	s_waitcnt lgkmcnt(0)
	v_pk_mul_f32 v[12:13], v[12:13], v[82:83]
	v_pk_mul_f32 v[8:9], v[8:9], v[86:87]
	v_pk_mul_f32 v[4:5], v[4:5], v[90:91]
	v_pk_mul_f32 v[14:15], v[14:15], v[84:85]
	v_pk_mul_f32 v[10:11], v[10:11], v[88:89]
	v_pk_mul_f32 v[6:7], v[6:7], v[92:93]
	v_pk_mul_f32 v[2:3], v[2:3], v[170:171]
	v_pk_mul_f32 v[0:1], v[0:1], v[168:169]
	v_pk_mul_f32 v[60:61], v[60:61], v[82:83]
	v_pk_mul_f32 v[56:57], v[56:57], v[86:87]
	v_pk_mul_f32 v[52:53], v[52:53], v[90:91]
	v_pk_mul_f32 v[62:63], v[62:63], v[84:85]
	v_pk_mul_f32 v[58:59], v[58:59], v[88:89]
	v_pk_mul_f32 v[54:55], v[54:55], v[92:93]
	v_pk_mul_f32 v[50:51], v[50:51], v[170:171]
	v_pk_mul_f32 v[48:49], v[48:49], v[168:169]
	v_pk_mul_f32 v[44:45], v[44:45], v[82:83]
	v_pk_mul_f32 v[40:41], v[40:41], v[86:87]
	v_pk_mul_f32 v[36:37], v[36:37], v[90:91]
	v_pk_mul_f32 v[46:47], v[46:47], v[84:85]
	v_pk_mul_f32 v[42:43], v[42:43], v[88:89]
	v_pk_mul_f32 v[38:39], v[38:39], v[92:93]
	v_pk_mul_f32 v[34:35], v[34:35], v[170:171]
	v_pk_mul_f32 v[32:33], v[32:33], v[168:169]
	v_pk_mul_f32 v[28:29], v[28:29], v[82:83]
	v_pk_mul_f32 v[24:25], v[24:25], v[86:87]
	v_pk_mul_f32 v[20:21], v[20:21], v[90:91]
	v_pk_mul_f32 v[30:31], v[30:31], v[84:85]
	v_pk_mul_f32 v[26:27], v[26:27], v[88:89]
	v_pk_mul_f32 v[22:23], v[22:23], v[92:93]
	v_pk_mul_f32 v[18:19], v[18:19], v[170:171]
	v_pk_mul_f32 v[16:17], v[16:17], v[168:169]
